# attention: end-of-round barrier moved up to right after the last PV MFMA; o scaling/stores/lse run in the next interval
# baseline (speedup 1.0000x reference)
; __device__ __forceinline__ void attn_phase(LAS unsigned char* lds, bf16_t* qkv, float* lse, const float* biasT, int G) {
;     ...
;     for (int j = 0; j < nrounds; ++j) {
;         const int pair = attn_pair(j, cwg, G); if (pair >= 4608) break;
;         const int pairn = (j + 1 < nrounds) ? attn_pair(j + 1, cwg, G) : 4608;
;         const AttnItem a = attn_item(pair * 2 + half);
;     ...
;         __syncthreads();
.LBB0_412:
	s_or_b64 exec, exec, s[0:1]
	v_readlane_b32 s0, v251, 30
	s_add_i32 s10, s97, s0
	v_readlane_b32 s0, v251, 11
	s_cmp_eq_u32 s0, s8
	s_cselect_b64 s[0:1], -1, 0
.LBB0_413:
	s_and_b64 vcc, exec, s[0:1]
	s_mov_b32 s97, s10
	s_mov_b32 s9, s8
	s_cbranch_vccnz .Lattn_exit

; #define LAS __attribute__((address_space(3)))
; __device__ __forceinline__ unsigned cvt_pk_bf16(float lo, float hi) { const bf16x2_t r = __builtin_convertvector((f32x2_t){lo, hi}, bf16x2_t); return __builtin_bit_cast(unsigned, r); }
; __device__ __forceinline__ void attn_phase(LAS unsigned char* lds, bf16_t* qkv, float* lse, const float* biasT, int G) {
;     ...
;         mx = fmaxf(mx, __shfl_xor(mx, 16)); mx = fmaxf(mx, __shfl_xor(mx, 32));
;         float sum = 0.f;
; #pragma unroll
;         for (int t9 = 0; t9 < 9; ++t9)
; #pragma unroll
;             for (int j = 0; j < 4; ++j) { const float pv = __builtin_amdgcn_exp2f(sa[t9][j] - mx); sa[t9][j] = pv; sum += pv; }
;         sum += __shfl_xor(sum, 16); sum += __shfl_xor(sum, 32);
;         bf16x8 Pf[5];
; #pragma unroll
;         for (int s5 = 0; s5 < 5; ++s5) {
;             u32x4 w; w.x = cvt_pk_bf16(sa[2 * s5][0], sa[2 * s5][1]); w.y = cvt_pk_bf16(sa[2 * s5][2], sa[2 * s5][3]);
;             w.z = cvt_pk_bf16(sa[2 * s5 + 1][0], sa[2 * s5 + 1][1]); w.w = cvt_pk_bf16(sa[2 * s5 + 1][2], sa[2 * s5 + 1][3]);
;             Pf[s5] = __builtin_bit_cast(bf16x8, w);
;         }
;         const float inv = 1.0f / sum;
;         f32x4 o[8];
; #pragma unroll
;         for (int dt = 0; dt < 8; ++dt) o[dt] = (f32x4){0.f, 0.f, 0.f, 0.f};
; #pragma unroll
;         for (int s5 = 0; s5 < 5; ++s5) {
;             s16x4 va[8], vb[8];
; #pragma unroll
;             for (int dt = 0; dt < 8; ++dt) {
;                 va[dt] = __builtin_amdgcn_ds_read_tr16_b64_v4i16((LAS s16x4*)(vrd + (32 * s5) * VS_PITCH + 32 * dt));
;                 vb[dt] = __builtin_amdgcn_ds_read_tr16_b64_v4i16((LAS s16x4*)(vrd + (32 * s5 + 16) * VS_PITCH + 32 * dt));
;             }
; #pragma unroll
;             for (int dt = 0; dt < 8; ++dt) {
;                 const bf16x8 Vf = (bf16x8){va[dt][0], va[dt][1], va[dt][2], va[dt][3], vb[dt][0], vb[dt][1], vb[dt][2], vb[dt][3]};
;                 o[dt] = __builtin_amdgcn_mfma_f32_16x16x32_bf16(Vf, Pf[s5], o[dt], 0, 0, 0);
;             }
.LBB0_455:
	s_nop 3
	ds_read_b32 v52, v218 offset:588
	v_and_b32_e32 v56, 64, v202
	v_xor_b32_e32 v54, 16, v202
	v_add_u32_e32 v56, 64, v56
	v_max_f32_e32 v53, v124, v124
	s_waitcnt lgkmcnt(0)
	v_fmac_f32_e32 v52, 0x3e0293ee, v55
	v_cndmask_b32_e64 v55, v212, v52, s[0:1]
	v_cmp_lt_i32_e32 vcc, v54, v56
	v_max_f32_e32 v52, v53, v55
	v_mov_b32_e32 v193, v1
	v_cndmask_b32_e32 v53, v202, v54, vcc
	v_lshlrev_b32_e32 v117, 2, v53
	ds_bpermute_b32 v53, v117, v52
	v_xor_b32_e32 v54, 32, v202
	v_cmp_lt_i32_e32 vcc, v54, v56
	s_waitcnt lgkmcnt(0)
	v_max_f32_e32 v53, v53, v53
	v_max_f32_e32 v57, v52, v53
	v_cndmask_b32_e32 v52, v202, v54, vcc
	v_lshlrev_b32_e32 v136, 2, v52
	ds_bpermute_b32 v54, v136, v57
	ds_read_b64_tr_b16 v[52:53], v219 offset:36864
	s_waitcnt lgkmcnt(1)
	v_max_f32_e32 v54, v54, v54
	v_max_f32_e32 v116, v57, v54
	v_sub_f32_e32 v54, v114, v116
	v_sub_f32_e32 v62, v120, v116
	v_exp_f32_e32 v54, v54
	v_sub_f32_e32 v0, v0, v116
	v_exp_f32_e32 v63, v62
	v_sub_f32_e32 v62, v88, v116
	v_exp_f32_e32 v0, v0
	v_sub_f32_e32 v59, v115, v116
	v_exp_f32_e32 v65, v62
	v_sub_f32_e32 v62, v89, v116
	v_exp_f32_e32 v59, v59
	v_exp_f32_e32 v74, v62
	v_sub_f32_e32 v62, v90, v116
	v_sub_f32_e32 v2, v2, v116
	v_exp_f32_e32 v114, v62
	v_sub_f32_e32 v62, v91, v116
	v_add_f32_e32 v58, 0, v54
	v_exp_f32_e32 v2, v2
	v_sub_f32_e32 v3, v3, v116
	v_exp_f32_e32 v115, v62
	v_sub_f32_e32 v62, v92, v116
	v_add_f32_e32 v58, v0, v58
	v_exp_f32_e32 v3, v3
	v_exp_f32_e32 v118, v62
	v_sub_f32_e32 v62, v93, v116
	v_add_f32_e32 v58, v59, v58
	v_exp_f32_e32 v119, v62
	v_sub_f32_e32 v62, v94, v116
	v_add_f32_e32 v58, v63, v58
	v_exp_f32_e32 v120, v62
	v_sub_f32_e32 v62, v95, v116
	v_add_f32_e32 v58, v2, v58
	v_exp_f32_e32 v124, v62
	v_sub_f32_e32 v62, v96, v116
	v_add_f32_e32 v58, v3, v58
	v_exp_f32_e32 v130, v62
	v_sub_f32_e32 v62, v97, v116
	v_add_f32_e32 v58, v65, v58
	v_exp_f32_e32 v131, v62
	v_sub_f32_e32 v62, v98, v116
	ds_read_b64_tr_b16 v[60:61], v219 offset:36896
	ds_read_b64_tr_b16 v[56:57], v219 offset:36928
	v_add_f32_e32 v58, v74, v58
	v_exp_f32_e32 v137, v62
	v_sub_f32_e32 v62, v99, v116
	ds_read_b64_tr_b16 v[68:69], v219 offset:4608
	ds_read_b64_tr_b16 v[66:67], v219
	ds_read_b64_tr_b16 v[70:71], v219 offset:32
	ds_read_b64_tr_b16 v[72:73], v219 offset:4640
	v_cvt_pk_bf16_f32 v65, v65, v74
	ds_read_b64_tr_b16 v[76:77], v219 offset:4672
	ds_read_b64_tr_b16 v[78:79], v219 offset:224
	ds_read_b64_tr_b16 v[74:75], v219 offset:64
	ds_read_b64_tr_b16 v[80:81], v219 offset:96
	ds_read_b64_tr_b16 v[82:83], v219 offset:4704
	ds_read_b64_tr_b16 v[86:87], v219 offset:4736
	v_exp_f32_e32 v138, v62
	v_sub_f32_e32 v62, v100, v116
	v_exp_f32_e32 v139, v62
	v_sub_f32_e32 v62, v101, v116
	v_exp_f32_e32 v140, v62
	v_sub_f32_e32 v62, v102, v116
	v_exp_f32_e32 v141, v62
	v_sub_f32_e32 v62, v103, v116
	v_exp_f32_e32 v142, v62
	v_sub_f32_e32 v62, v104, v116
	v_exp_f32_e32 v143, v62
	v_sub_f32_e32 v62, v105, v116
	v_exp_f32_e32 v144, v62
	v_sub_f32_e32 v62, v106, v116
	v_exp_f32_e32 v145, v62
	v_cvt_pk_bf16_f32 v62, v54, v0
	v_cvt_pk_bf16_f32 v63, v59, v63
	v_cvt_pk_bf16_f32 v64, v2, v3
	ds_read_b64_tr_b16 v[84:85], v219 offset:128
	ds_read_b64_tr_b16 v[88:89], v219 offset:160
	ds_read_b64_tr_b16 v[92:93], v219 offset:192
	ds_read_b64_tr_b16 v[90:91], v219 offset:4768
	ds_read_b64_tr_b16 v[94:95], v219 offset:4800
	s_waitcnt lgkmcnt(6)
	v_mfma_f32_16x16x32_bf16 v[96:99], v[80:83], v[62:65], 0
	ds_read_b64_tr_b16 v[80:81], v219 offset:4832
	v_add_f32_e32 v58, v114, v58
	v_add_f32_e32 v58, v115, v58
	v_add_f32_e32 v58, v118, v58
	v_sub_f32_e32 v0, v107, v116
	ds_read_b64_tr_b16 v[104:105], v219 offset:9216
	ds_read_b64_tr_b16 v[106:107], v219 offset:13824
	v_add_f32_e32 v58, v119, v58
	v_mfma_f32_16x16x32_bf16 v[66:69], v[66:69], v[62:65], 0
	v_add_f32_e32 v58, v120, v58
	v_add_f32_e32 v58, v124, v58
	v_add_f32_e32 v58, v130, v58
	s_waitcnt lgkmcnt(7)
	v_mfma_f32_16x16x32_bf16 v[82:85], v[84:87], v[62:65], 0
	v_cvt_pk_bf16_f32 v86, v114, v115
	v_cvt_pk_bf16_f32 v87, v118, v119
	v_add_f32_e32 v58, v131, v58
	s_waitcnt lgkmcnt(4)
	v_mfma_f32_16x16x32_bf16 v[100:103], v[88:91], v[62:65], 0
	v_cvt_pk_bf16_f32 v88, v120, v124
	v_cvt_pk_bf16_f32 v89, v130, v131
	ds_read_b64_tr_b16 v[126:127], v219 offset:13856
	ds_read_b64_tr_b16 v[124:125], v219 offset:9248
	ds_read_b64_tr_b16 v[128:129], v219 offset:9280
	v_mfma_f32_16x16x32_bf16 v[70:73], v[70:73], v[62:65], 0
	v_sub_f32_e32 v3, v108, v116
	v_sub_f32_e32 v54, v109, v116
	v_add_f32_e32 v58, v137, v58
	v_mfma_f32_16x16x32_bf16 v[74:77], v[74:77], v[62:65], 0
	v_add_f32_e32 v58, v138, v58
	v_add_f32_e32 v58, v139, v58
	v_add_f32_e32 v58, v140, v58
	s_waitcnt lgkmcnt(6)
	v_mfma_f32_16x16x32_bf16 v[90:93], v[92:95], v[62:65], 0
	v_add_f32_e32 v58, v141, v58
	v_add_f32_e32 v58, v142, v58
	v_exp_f32_e32 v0, v0
	s_waitcnt lgkmcnt(5)
	v_mfma_f32_16x16x32_bf16 v[62:65], v[78:81], v[62:65], 0
	ds_read_b64_tr_b16 v[130:131], v219 offset:13888
	ds_read_b64_tr_b16 v[78:79], v219 offset:9440
	v_add_f32_e32 v58, v143, v58
	v_add_f32_e32 v58, v144, v58
	s_waitcnt lgkmcnt(5)
	v_mfma_f32_16x16x32_bf16 v[66:69], v[104:107], v[86:89], v[66:69]
	ds_read_b64_tr_b16 v[104:105], v219 offset:9312
	ds_read_b64_tr_b16 v[106:107], v219 offset:13920
	v_add_f32_e32 v58, v145, v58
	s_waitcnt lgkmcnt(5)
	v_mfma_f32_16x16x32_bf16 v[70:73], v[124:127], v[86:89], v[70:73]
	ds_read_b64_tr_b16 v[126:127], v219 offset:13952
	v_add_f32_e32 v2, v0, v58
	v_sub_f32_e32 v58, v110, v116
	s_waitcnt lgkmcnt(4)
; #define LAS __attribute__((address_space(3)))
; __device__ __forceinline__ unsigned cvt_pk_bf16(float lo, float hi) { const bf16x2_t r = __builtin_convertvector((f32x2_t){lo, hi}, bf16x2_t); return __builtin_bit_cast(unsigned, r); }
; __device__ __forceinline__ void attn_phase(LAS unsigned char* lds, bf16_t* qkv, float* lse, const float* biasT, int G) {
;     ...
;         sum += __shfl_xor(sum, 16); sum += __shfl_xor(sum, 32);
;         bf16x8 Pf[5];
; #pragma unroll
;         for (int s5 = 0; s5 < 5; ++s5) {
;             u32x4 w; w.x = cvt_pk_bf16(sa[2 * s5][0], sa[2 * s5][1]); w.y = cvt_pk_bf16(sa[2 * s5][2], sa[2 * s5][3]);
;             w.z = cvt_pk_bf16(sa[2 * s5 + 1][0], sa[2 * s5 + 1][1]); w.w = cvt_pk_bf16(sa[2 * s5 + 1][2], sa[2 * s5 + 1][3]);
;             Pf[s5] = __builtin_bit_cast(bf16x8, w);
;         }
;         const float inv = 1.0f / sum;
;         f32x4 o[8];
; #pragma unroll
;         for (int dt = 0; dt < 8; ++dt) o[dt] = (f32x4){0.f, 0.f, 0.f, 0.f};
; #pragma unroll
;         for (int s5 = 0; s5 < 5; ++s5) {
;             s16x4 va[8], vb[8];
; #pragma unroll
;             for (int dt = 0; dt < 8; ++dt) {
;                 va[dt] = __builtin_amdgcn_ds_read_tr16_b64_v4i16((LAS s16x4*)(vrd + (32 * s5) * VS_PITCH + 32 * dt));
;                 vb[dt] = __builtin_amdgcn_ds_read_tr16_b64_v4i16((LAS s16x4*)(vrd + (32 * s5 + 16) * VS_PITCH + 32 * dt));
;             }
; #pragma unroll
;             for (int dt = 0; dt < 8; ++dt) {
;                 const bf16x8 Vf = (bf16x8){va[dt][0], va[dt][1], va[dt][2], va[dt][3], vb[dt][0], vb[dt][1], vb[dt][2], vb[dt][3]};
;                 o[dt] = __builtin_amdgcn_mfma_f32_16x16x32_bf16(Vf, Pf[s5], o[dt], 0, 0, 0);
;             }
;         }
;     ...
;         __syncthreads();
	v_mfma_f32_16x16x32_bf16 v[74:77], v[128:131], v[86:89], v[74:77]
	ds_read_b64_tr_b16 v[124:125], v219 offset:9344
	ds_read_b64_tr_b16 v[128:129], v219 offset:9376
	ds_read_b64_tr_b16 v[132:133], v219 offset:9408
	ds_read_b64_tr_b16 v[130:131], v219 offset:13984
	ds_read_b64_tr_b16 v[134:135], v219 offset:14016
	ds_read_b64_tr_b16 v[80:81], v219 offset:14048
	v_sub_f32_e32 v59, v111, v116
	s_waitcnt lgkmcnt(7)
	v_mfma_f32_16x16x32_bf16 v[94:97], v[104:107], v[86:89], v[96:99]
	ds_read_b64_tr_b16 v[106:107], v219 offset:18432
	ds_read_b64_tr_b16 v[108:109], v219 offset:23040
	v_exp_f32_e32 v3, v3
	v_cvt_pk_bf16_f32 v98, v137, v138
	v_cvt_pk_bf16_f32 v99, v139, v140
	s_waitcnt lgkmcnt(4)
	v_mfma_f32_16x16x32_bf16 v[102:105], v[128:131], v[86:89], v[100:103]
	v_exp_f32_e32 v54, v54
	v_exp_f32_e32 v58, v58
	v_exp_f32_e32 v59, v59
	v_cvt_pk_bf16_f32 v100, v141, v142
	v_cvt_pk_bf16_f32 v101, v143, v144
	v_mfma_f32_16x16x32_bf16 v[82:85], v[124:127], v[86:89], v[82:85]
	ds_read_b64_tr_b16 v[126:127], v219 offset:23072
	ds_read_b64_tr_b16 v[124:125], v219 offset:18464
	ds_read_b64_tr_b16 v[128:129], v219 offset:18496
	v_add_f32_e32 v2, v3, v2
	v_add_f32_e32 v2, v54, v2
	s_waitcnt lgkmcnt(6)
	v_mfma_f32_16x16x32_bf16 v[90:93], v[132:135], v[86:89], v[90:93]
	v_add_f32_e32 v2, v58, v2
	s_waitcnt lgkmcnt(5)
	v_mfma_f32_16x16x32_bf16 v[62:65], v[78:81], v[86:89], v[62:65]
	ds_read_b64_tr_b16 v[130:131], v219 offset:23104
	ds_read_b64_tr_b16 v[78:79], v219 offset:18656
	ds_read_b64_tr_b16 v[86:87], v219 offset:18528
	ds_read_b64_tr_b16 v[88:89], v219 offset:23136
	s_waitcnt lgkmcnt(7)
	v_mfma_f32_16x16x32_bf16 v[66:69], v[106:109], v[98:101], v[66:69]
	ds_read_b64_tr_b16 v[108:109], v219 offset:23168
	v_sub_f32_e32 v80, v112, v116
	v_exp_f32_e32 v114, v80
	v_sub_f32_e32 v80, v113, v116
	s_waitcnt lgkmcnt(6)
	v_mfma_f32_16x16x32_bf16 v[70:73], v[124:127], v[98:101], v[70:73]
	v_exp_f32_e32 v115, v80
	s_waitcnt lgkmcnt(4)
	v_mfma_f32_16x16x32_bf16 v[74:77], v[128:131], v[98:101], v[74:77]
	ds_read_b64_tr_b16 v[106:107], v219 offset:18560
	ds_read_b64_tr_b16 v[124:125], v219 offset:18592
	ds_read_b64_tr_b16 v[128:129], v219 offset:18624
	ds_read_b64_tr_b16 v[126:127], v219 offset:23200
	ds_read_b64_tr_b16 v[130:131], v219 offset:23232
	ds_read_b64_tr_b16 v[80:81], v219 offset:23264
	s_waitcnt lgkmcnt(5)
	v_mfma_f32_16x16x32_bf16 v[82:85], v[106:109], v[98:101], v[82:85]
	ds_read_b64_tr_b16 v[106:107], v219 offset:27648
	ds_read_b64_tr_b16 v[108:109], v219 offset:32256
	s_waitcnt lgkmcnt(4)
	v_mfma_f32_16x16x32_bf16 v[102:105], v[124:127], v[98:101], v[102:105]
	s_waitcnt lgkmcnt(3)
	v_mfma_f32_16x16x32_bf16 v[110:113], v[128:131], v[98:101], v[90:93]
	s_nop 2
	ds_read_b64_tr_b16 v[92:93], v219 offset:32288
	ds_read_b64_tr_b16 v[90:91], v219 offset:27680
	ds_read_b64_tr_b16 v[124:125], v219 offset:27712
	v_mfma_f32_16x16x32_bf16 v[86:89], v[86:89], v[98:101], v[94:97]
	s_nop 2
	v_cvt_pk_bf16_f32 v94, v145, v0
	v_cvt_pk_bf16_f32 v95, v3, v54
	v_cvt_pk_bf16_f32 v96, v58, v59
	v_cvt_pk_bf16_f32 v97, v114, v115
	s_waitcnt lgkmcnt(5)
	v_mfma_f32_16x16x32_bf16 v[98:101], v[78:81], v[98:101], v[62:65]
	ds_read_b64_tr_b16 v[126:127], v219 offset:32320
	s_nop 1
	ds_read_b64_tr_b16 v[64:65], v219 offset:27872
	v_sub_f32_e32 v54, v123, v116
	v_sub_f32_e32 v3, v121, v116
	s_waitcnt lgkmcnt(5)
	v_mfma_f32_16x16x32_bf16 v[106:109], v[106:109], v[94:97], v[66:69]
	s_nop 2
	ds_read_b64_tr_b16 v[66:67], v219 offset:27744
	ds_read_b64_tr_b16 v[68:69], v219 offset:32352
	v_add_f32_e32 v0, v59, v2
	v_sub_f32_e32 v2, v122, v116
	s_waitcnt lgkmcnt(5)
	v_mfma_f32_16x16x32_bf16 v[128:131], v[90:93], v[94:97], v[70:73]
	s_nop 2
	ds_read_b64_tr_b16 v[72:73], v219 offset:32384
	ds_read_b64_tr_b16 v[70:71], v219 offset:27776
	v_exp_f32_e32 v2, v2
	v_exp_f32_e32 v3, v3
	s_waitcnt lgkmcnt(0)
	v_mfma_f32_16x16x32_bf16 v[118:121], v[70:73], v[94:97], v[82:85]
	v_add_f32_e32 v0, v114, v0
	s_nop 1
	v_exp_f32_e32 v84, v54
	v_sub_f32_e32 v54, v55, v116
	v_mfma_f32_16x16x32_bf16 v[124:127], v[124:127], v[94:97], v[74:77]
	s_nop 2
	ds_read_b64_tr_b16 v[74:75], v219 offset:27808
	ds_read_b64_tr_b16 v[78:79], v219 offset:27840
	ds_read_b64_tr_b16 v[76:77], v219 offset:32416
	ds_read_b64_tr_b16 v[80:81], v219 offset:32448
	ds_read_b64_tr_b16 v[62:63], v219 offset:41504
	ds_read_b64_tr_b16 v[58:59], v219 offset:41536
	v_mfma_f32_16x16x32_bf16 v[132:135], v[66:69], v[94:97], v[86:89]
	ds_read_b64_tr_b16 v[66:67], v219 offset:32480
	v_exp_f32_e32 v85, v54
	ds_read_b64_tr_b16 v[54:55], v219 offset:41472
	v_add_f32_e32 v0, v115, v0
	v_add_f32_e32 v0, v2, v0
	v_add_f32_e32 v0, v3, v0
	s_waitcnt lgkmcnt(5)
	v_mfma_f32_16x16x32_bf16 v[88:91], v[74:77], v[94:97], v[102:105]
	v_cvt_pk_bf16_f32 v72, v2, v3
	v_cvt_pk_bf16_f32 v73, v84, v85
	v_mov_b32_e32 v74, v1
	v_mov_b32_e32 v75, v1
	v_add_f32_e32 v0, v84, v0
	s_waitcnt lgkmcnt(4)
	v_mfma_f32_16x16x32_bf16 v[80:83], v[78:81], v[94:97], v[110:113]
	v_add_f32_e32 v0, v85, v0
	ds_bpermute_b32 v2, v117, v0
	s_waitcnt lgkmcnt(0)
	v_add_f32_e32 v0, v0, v2
	v_mfma_f32_16x16x32_bf16 v[76:79], v[64:67], v[94:97], v[98:101]
	ds_bpermute_b32 v2, v136, v0
	s_waitcnt lgkmcnt(0)
	v_add_f32_e32 v0, v0, v2
	v_mfma_f32_16x16x32_bf16 v[68:71], v[52:55], v[72:75], v[106:109]
	ds_read_b64_tr_b16 v[52:53], v219 offset:36960
	ds_read_b64_tr_b16 v[54:55], v219 offset:41568
	ds_read_b64_tr_b16 v[98:99], v219 offset:41600
	ds_read_b64_tr_b16 v[96:97], v219 offset:36992
	ds_read_b64_tr_b16 v[92:93], v219 offset:37024
	ds_read_b64_tr_b16 v[94:95], v219 offset:41632
	v_mfma_f32_16x16x32_bf16 v[64:67], v[60:63], v[72:75], v[128:131]
	ds_read_b64_tr_b16 v[84:85], v219 offset:37056
	ds_read_b64_tr_b16 v[86:87], v219 offset:41664
	v_div_scale_f32 v2, s[0:1], v0, v0, 1.0
	v_mfma_f32_16x16x32_bf16 v[60:63], v[56:59], v[72:75], v[124:127]
	v_rcp_f32_e32 v3, v2
	s_waitcnt lgkmcnt(6)
	v_mfma_f32_16x16x32_bf16 v[56:59], v[52:55], v[72:75], v[132:135]
	s_waitcnt lgkmcnt(4)
	v_mfma_f32_16x16x32_bf16 v[52:55], v[96:99], v[72:75], v[118:121]
	ds_read_b64_tr_b16 v[96:97], v219 offset:41696
	s_waitcnt lgkmcnt(3)
	v_mfma_f32_16x16x32_bf16 v[88:91], v[92:95], v[72:75], v[88:91]
	ds_read_b64_tr_b16 v[94:95], v219 offset:37088
	s_waitcnt lgkmcnt(2)
	v_mfma_f32_16x16x32_bf16 v[80:83], v[84:87], v[72:75], v[80:83]
	s_waitcnt lgkmcnt(0)
	v_mfma_f32_16x16x32_bf16 v[72:75], v[94:97], v[72:75], v[76:79]
	s_barrier
; __device__ __forceinline__ unsigned cvt_pk_bf16(float lo, float hi) { const bf16x2_t r = __builtin_convertvector((f32x2_t){lo, hi}, bf16x2_t); return __builtin_bit_cast(unsigned, r); }
; __device__ __forceinline__ void attn_phase(LAS unsigned char* lds, bf16_t* qkv, float* lse, const float* biasT, int G) {
;     ...
; #pragma unroll
;         for (int dt = 0; dt < 8; ++dt) {
;             const f32x4 ov = o[dt] * inv;
;             u32x2 w; w.x = cvt_pk_bf16(ov[0], ov[1]); w.y = cvt_pk_bf16(ov[2], ov[3]);
;             *(u32x2*)(qp + 16 * dt + 4 * lg) = w;
;         }
;         if (lg == 0) lse[tokq * 12 + a.head] = (mx + __log2f(sum)) * 0.6931471805599453f;
	s_nop 2
	v_fma_f32 v76, -v2, v3, 1.0
	v_fmac_f32_e32 v3, v76, v3
	v_div_scale_f32 v76, vcc, 1.0, v0, 1.0
	v_mul_f32_e32 v77, v76, v3
	v_fma_f32 v78, -v2, v77, v76
	v_fmac_f32_e32 v77, v78, v3
	v_fma_f32 v2, -v2, v77, v76
	v_div_fmas_f32 v2, v2, v3, v77
	v_div_fixup_f32 v2, v2, v0, 1.0
	v_pk_mul_f32 v[54:55], v[2:3], v[54:55] op_sel_hi:[0,1]
	v_pk_mul_f32 v[52:53], v[2:3], v[52:53] op_sel_hi:[0,1]
	v_lshl_add_u64 v[76:77], v[194:195], 0, v[192:193]
	v_cvt_pk_bf16_f32 v52, v52, v53
	v_cvt_pk_bf16_f32 v53, v54, v55
	global_store_dwordx2 v[76:77], v[52:53], off offset:128
	v_pk_mul_f32 v[52:53], v[2:3], v[90:91] op_sel_hi:[0,1]
	v_pk_mul_f32 v[54:55], v[2:3], v[88:89] op_sel_hi:[0,1]
	v_cvt_pk_bf16_f32 v54, v54, v55
	v_cvt_pk_bf16_f32 v55, v52, v53
	global_store_dwordx2 v[76:77], v[54:55], off offset:160
	v_pk_mul_f32 v[52:53], v[2:3], v[82:83] op_sel_hi:[0,1]
	v_pk_mul_f32 v[54:55], v[2:3], v[80:81] op_sel_hi:[0,1]
	v_pk_mul_f32 v[70:71], v[2:3], v[70:71] op_sel_hi:[0,1]
	v_pk_mul_f32 v[68:69], v[2:3], v[68:69] op_sel_hi:[0,1]
	v_pk_mul_f32 v[66:67], v[2:3], v[66:67] op_sel_hi:[0,1]
	v_pk_mul_f32 v[64:65], v[2:3], v[64:65] op_sel_hi:[0,1]
	v_pk_mul_f32 v[62:63], v[2:3], v[62:63] op_sel_hi:[0,1]
	v_pk_mul_f32 v[60:61], v[2:3], v[60:61] op_sel_hi:[0,1]
	v_pk_mul_f32 v[58:59], v[2:3], v[58:59] op_sel_hi:[0,1]
	v_pk_mul_f32 v[56:57], v[2:3], v[56:57] op_sel_hi:[0,1]
	v_cvt_pk_bf16_f32 v54, v54, v55
	v_cvt_pk_bf16_f32 v55, v52, v53
	v_pk_mul_f32 v[52:53], v[2:3], v[74:75] op_sel_hi:[0,1]
	v_pk_mul_f32 v[2:3], v[2:3], v[72:73] op_sel_hi:[0,1]
	v_cvt_pk_bf16_f32 v68, v68, v69
	v_cvt_pk_bf16_f32 v69, v70, v71
	v_cvt_pk_bf16_f32 v64, v64, v65
	v_cvt_pk_bf16_f32 v65, v66, v67
	v_cvt_pk_bf16_f32 v60, v60, v61
	v_cvt_pk_bf16_f32 v61, v62, v63
	v_cvt_pk_bf16_f32 v56, v56, v57
	v_cvt_pk_bf16_f32 v57, v58, v59
	v_cvt_pk_bf16_f32 v2, v2, v3
	v_cvt_pk_bf16_f32 v3, v52, v53
	global_store_dwordx2 v[76:77], v[68:69], off
	global_store_dwordx2 v[76:77], v[64:65], off offset:32
	global_store_dwordx2 v[76:77], v[60:61], off offset:64
	global_store_dwordx2 v[76:77], v[56:57], off offset:96
	global_store_dwordx2 v[76:77], v[54:55], off offset:192
	global_store_dwordx2 v[76:77], v[2:3], off offset:224
	s_and_saveexec_b64 s[0:1], s[26:27]
	s_cbranch_execz .LBB0_412
	s_lshl_b32 s13, s13, s12
	v_lshlrev_b32_e32 v2, s12, v184
	v_log_f32_e32 v0, v0
	s_add_i32 s12, s13, s96
	s_add_i32 s12, s12, s9
	v_add_u32_e32 v2, s12, v2
	v_readlane_b32 s12, v250, 15
	v_readlane_b32 s13, v250, 16
	v_add_f32_e32 v0, v116, v0
	v_mul_f32_e32 v0, 0x3f317218, v0
	v_mad_i64_i32 v[2:3], s[12:13], v2, 48, s[12:13]
	v_lshl_add_u64 v[2:3], s[10:11], 2, v[2:3]
	global_store_dword v[2:3], v0, off
	s_branch .LBB0_412
